# SGU mix staging: the 8 v-row loads and the 8 W_s loads of a thread are each issued together with one wait instead of load-wait-LDS-write chains
# speedup vs baseline: 1.0086x; 1.0017x over previous
; #define LAS __attribute__((address_space(3)))
; __device__ __forceinline__ void mix_phase(const int TID, const int BID, PP p, LAS unsigned char* lds) {
;     ...
;         { const int j = t & 127, cgp = t >> 7; const bf16_t* vsrc = uv + (size_t)(n * 128 + j) * 4096 + 2048 + g * 256;
; #pragma unroll
;           for (int q = 0; q < 8; ++q) {
;               const int c = (q * 4 + cgp) * 8; const u32x4 v = *(const u32x4*)(vsrc + c);
; #pragma unroll
;               for (int e = 0; e < 4; ++e) { *(LAS bf16_t*)(Vt + (c + 2 * e) * 272 + j * 2) = (bf16_t)(v[e] & 0xffffu); *(LAS bf16_t*)(Vt + (c + 2 * e + 1) * 272 + j * 2) = (bf16_t)(v[e] >> 16); }
;           } }
.LBB0_834:
	s_or_b64 exec, exec, s[10:11]
	ds_write_b128 v89, v[0:3] offset:1024
	v_lshl_or_b32 v0, s18, 7, v75
	v_ashrrev_i32_e32 v1, 31, v0
	v_lshlrev_b64 v[0:1], 13, v[0:1]
	v_lshl_add_u64 v[0:1], s[14:15], 0, v[0:1]
	s_lshl_b32 s10, s0, 9
	s_mov_b32 s11, s73
	v_lshl_add_u64 v[0:1], v[0:1], 0, s[10:11]
	v_lshl_add_u64 v[2:3], v[68:69], 1, v[0:1]
	s_mov_b64 s[10:11], 0x1000
	s_movk_i32 s1, 0x1000
	v_lshl_add_u64 v[0:1], v[2:3], 0, s[10:11]
	v_add_co_u32_e64 v2, s[10:11], s1, v2
	v_add_u32_e32 v6, v85, v77
	s_nop 0
	v_addc_co_u32_e64 v3, s[10:11], 0, v3, s[10:11]
	global_load_dwordx4 v[208:211], v[2:3], off
	global_load_dwordx4 v[212:215], v[0:1], off offset:64
	global_load_dwordx4 v[216:219], v[0:1], off offset:128
	global_load_dwordx4 v[220:223], v[0:1], off offset:192
	global_load_dwordx4 v[224:227], v[0:1], off offset:256
	global_load_dwordx4 v[228:231], v[0:1], off offset:320
	global_load_dwordx4 v[232:235], v[0:1], off offset:384
	global_load_dwordx4 v[236:239], v[0:1], off offset:448
	v_readlane_b32 s10, v254, 32
	v_readlane_b32 s11, v254, 33
	s_ashr_i32 s19, s18, 31
	s_lshl_b64 s[18:19], s[18:19], 7
	v_mov_b32_e32 v117, s19
	v_or_b32_e32 v116, s18, v72
	s_add_i32 s22, s22, s70
	s_cmpk_gt_i32 s22, 0x1ff
	s_waitcnt vmcnt(0)
	v_mov_b64_e32 v[2:3], v[208:209]
	v_mov_b64_e32 v[4:5], v[210:211]
	ds_write_b16 v6, v2 offset:35840
	ds_write_b16_d16_hi v6, v2 offset:36112
	ds_write_b16 v6, v3 offset:36384
	ds_write_b16_d16_hi v6, v3 offset:36656
	ds_write_b16 v6, v4 offset:36928
	ds_write_b16_d16_hi v6, v4 offset:37200
	ds_write_b16 v6, v5 offset:37472
	ds_write_b16_d16_hi v6, v5 offset:37744
	v_mov_b64_e32 v[2:3], v[212:213]
	v_mov_b64_e32 v[4:5], v[214:215]
	ds_write_b16 v91, v2 offset:35840
	ds_write_b16_d16_hi v91, v2 offset:36112
	ds_write_b16 v6, v3 offset:45088
	ds_write_b16_d16_hi v6, v3 offset:45360
	ds_write_b16 v6, v4 offset:45632
	ds_write_b16_d16_hi v6, v4 offset:45904
	ds_write_b16 v6, v5 offset:46176
	ds_write_b16_d16_hi v6, v5 offset:46448
	v_mov_b64_e32 v[2:3], v[216:217]
	v_mov_b64_e32 v[4:5], v[218:219]
	ds_write_b16 v93, v2 offset:35840
	ds_write_b16_d16_hi v93, v2 offset:36112
	ds_write_b16 v6, v3 offset:53792
	ds_write_b16_d16_hi v6, v3 offset:54064
	ds_write_b16 v6, v4 offset:54336
	ds_write_b16_d16_hi v6, v4 offset:54608
	ds_write_b16 v6, v5 offset:54880
	ds_write_b16_d16_hi v6, v5 offset:55152
	v_mov_b64_e32 v[2:3], v[220:221]
	v_mov_b64_e32 v[4:5], v[222:223]
	ds_write_b16 v95, v2 offset:35840
	ds_write_b16_d16_hi v95, v2 offset:36112
	ds_write_b16 v6, v3 offset:62496
	ds_write_b16_d16_hi v6, v3 offset:62768
	ds_write_b16 v6, v4 offset:63040
	ds_write_b16_d16_hi v6, v4 offset:63312
	ds_write_b16 v6, v5 offset:63584
	ds_write_b16_d16_hi v6, v5 offset:63856
	v_mov_b64_e32 v[2:3], v[224:225]
	v_mov_b64_e32 v[4:5], v[226:227]
	ds_write_b16 v97, v2 offset:35840
	ds_write_b16_d16_hi v97, v2 offset:36112
	ds_write_b16 v99, v3 offset:35360
	ds_write_b16_d16_hi v99, v3 offset:35632
	ds_write_b16 v99, v4 offset:35904
	ds_write_b16_d16_hi v99, v4 offset:36176
	ds_write_b16 v99, v5 offset:36448
	ds_write_b16_d16_hi v99, v5 offset:36720
	v_mov_b64_e32 v[2:3], v[228:229]
	v_mov_b64_e32 v[4:5], v[230:231]
	ds_write_b16 v101, v2 offset:35840
	ds_write_b16_d16_hi v101, v2 offset:36112
	ds_write_b16 v99, v3 offset:44064
	ds_write_b16_d16_hi v99, v3 offset:44336
	ds_write_b16 v99, v4 offset:44608
	ds_write_b16_d16_hi v99, v4 offset:44880
	ds_write_b16 v99, v5 offset:45152
	ds_write_b16_d16_hi v99, v5 offset:45424
	v_mov_b64_e32 v[2:3], v[232:233]
	v_mov_b64_e32 v[4:5], v[234:235]
	ds_write_b16 v160, v2 offset:35840
	ds_write_b16_d16_hi v160, v2 offset:36112
	ds_write_b16 v99, v3 offset:52768
	ds_write_b16_d16_hi v99, v3 offset:53040
	ds_write_b16 v99, v4 offset:53312
	ds_write_b16_d16_hi v99, v4 offset:53584
	ds_write_b16 v99, v5 offset:53856
	ds_write_b16_d16_hi v99, v5 offset:54128
	v_mov_b64_e32 v[0:1], v[236:237]
	v_mov_b64_e32 v[2:3], v[238:239]
	ds_write_b16 v182, v0 offset:35840
	ds_write_b16_d16_hi v182, v0 offset:36112
	ds_write_b16 v99, v1 offset:61472
	ds_write_b16_d16_hi v99, v1 offset:61744
	ds_write_b16 v99, v2 offset:62016
	ds_write_b16_d16_hi v99, v2 offset:62288
	ds_write_b16 v99, v3 offset:62560
	ds_write_b16_d16_hi v99, v3 offset:62832
	s_waitcnt lgkmcnt(0)
	s_barrier
; #define LAS __attribute__((address_space(3)))
; __device__ __forceinline__ void mix_phase(const int TID, const int BID, PP p, LAS unsigned char* lds) {
;     ...
;         f32x16 acc[4];
; #pragma unroll
;         for (int ct = 0; ct < 4; ++ct)
; #pragma unroll
;             for (int i = 0; i < 16; ++i) acc[ct][i] = 0.f;
; #pragma unroll
;         for (int ks = 0; ks < 8; ++ks) {
;             const bf16x8 Af = *(const LAS bf16x8*)(Wsl + (it_ * 32 + rr) * 272 + (ks * 16 + g2 * 8) * 2);
; #pragma unroll
;             for (int ct = 0; ct < 4; ++ct) { const bf16x8 Bf = *(const LAS bf16x8*)(Vt + (ch * 128 + ct * 32 + rr) * 272 + (ks * 16 + g2 * 8) * 2); acc[ct] = __builtin_amdgcn_mfma_f32_32x32x16_bf16(Af, Bf, acc[ct], 0, 0, 0); }
;         }
	ds_read_b128 v[0:3], v183 offset:1024
	ds_read_b128 v[102:105], v183 offset:1056
	ds_read_b128 v[4:7], v184 offset:35840
	ds_read_b128 v[106:109], v184 offset:35872
	s_waitcnt lgkmcnt(1)
	v_mfma_f32_32x32x16_bf16 v[48:63], v[0:3], v[4:7], 0
	ds_read_b128 v[4:7], v184 offset:44544
	s_waitcnt lgkmcnt(1)
	v_mfma_f32_32x32x16_bf16 v[48:63], v[102:105], v[106:109], v[48:63]
	ds_read_b128 v[106:109], v184 offset:44576
	s_waitcnt lgkmcnt(1)
	v_mfma_f32_32x32x16_bf16 v[32:47], v[0:3], v[4:7], 0
	ds_read_b128 v[4:7], v184 offset:53248
	s_waitcnt lgkmcnt(1)
	v_mfma_f32_32x32x16_bf16 v[32:47], v[102:105], v[106:109], v[32:47]
	ds_read_b128 v[106:109], v184 offset:53280
	s_waitcnt lgkmcnt(1)
	v_mfma_f32_32x32x16_bf16 v[16:31], v[0:3], v[4:7], 0
	ds_read_b128 v[4:7], v184 offset:61952
	s_waitcnt lgkmcnt(1)
	v_mfma_f32_32x32x16_bf16 v[16:31], v[102:105], v[106:109], v[16:31]
	ds_read_b128 v[106:109], v184 offset:61984
	s_waitcnt lgkmcnt(1)
	v_mfma_f32_32x32x16_bf16 v[0:15], v[0:3], v[4:7], 0
	s_waitcnt lgkmcnt(0)
	v_mfma_f32_32x32x16_bf16 v[0:15], v[102:105], v[106:109], v[0:15]
	ds_read_b128 v[102:105], v183 offset:1088
	ds_read_b128 v[106:109], v184 offset:35904
	s_waitcnt lgkmcnt(0)
	v_mfma_f32_32x32x16_bf16 v[48:63], v[102:105], v[106:109], v[48:63]
	ds_read_b128 v[106:109], v184 offset:44608
	s_waitcnt lgkmcnt(0)
	v_mfma_f32_32x32x16_bf16 v[32:47], v[102:105], v[106:109], v[32:47]
	ds_read_b128 v[106:109], v184 offset:53312
	s_waitcnt lgkmcnt(0)
	v_mfma_f32_32x32x16_bf16 v[16:31], v[102:105], v[106:109], v[16:31]
	ds_read_b128 v[106:109], v184 offset:62016
	s_waitcnt lgkmcnt(0)
	v_mfma_f32_32x32x16_bf16 v[0:15], v[102:105], v[106:109], v[0:15]
	ds_read_b128 v[102:105], v183 offset:1120
	ds_read_b128 v[106:109], v184 offset:35936
	s_waitcnt lgkmcnt(0)
	v_mfma_f32_32x32x16_bf16 v[48:63], v[102:105], v[106:109], v[48:63]
	ds_read_b128 v[106:109], v184 offset:44640
	s_waitcnt lgkmcnt(0)
	v_mfma_f32_32x32x16_bf16 v[32:47], v[102:105], v[106:109], v[32:47]
	ds_read_b128 v[106:109], v184 offset:53344
	s_waitcnt lgkmcnt(0)
	v_mfma_f32_32x32x16_bf16 v[16:31], v[102:105], v[106:109], v[16:31]
	ds_read_b128 v[106:109], v184 offset:62048
	s_waitcnt lgkmcnt(0)
	v_mfma_f32_32x32x16_bf16 v[0:15], v[102:105], v[106:109], v[0:15]
	ds_read_b128 v[102:105], v183 offset:1152
	ds_read_b128 v[106:109], v184 offset:35968
	s_waitcnt lgkmcnt(0)
	v_mfma_f32_32x32x16_bf16 v[48:63], v[102:105], v[106:109], v[48:63]
	ds_read_b128 v[106:109], v184 offset:44672
	s_waitcnt lgkmcnt(0)
	v_mfma_f32_32x32x16_bf16 v[32:47], v[102:105], v[106:109], v[32:47]
	ds_read_b128 v[106:109], v184 offset:53376
	s_waitcnt lgkmcnt(0)
	v_mfma_f32_32x32x16_bf16 v[16:31], v[102:105], v[106:109], v[16:31]
	ds_read_b128 v[106:109], v184 offset:62080
	s_waitcnt lgkmcnt(0)
	v_mfma_f32_32x32x16_bf16 v[0:15], v[102:105], v[106:109], v[0:15]
	ds_read_b128 v[102:105], v183 offset:1184
	ds_read_b128 v[106:109], v184 offset:36000
	s_waitcnt lgkmcnt(0)
	v_mfma_f32_32x32x16_bf16 v[48:63], v[102:105], v[106:109], v[48:63]
	ds_read_b128 v[106:109], v184 offset:44704
	s_waitcnt lgkmcnt(0)
	v_mfma_f32_32x32x16_bf16 v[32:47], v[102:105], v[106:109], v[32:47]
	ds_read_b128 v[106:109], v184 offset:53408
	s_waitcnt lgkmcnt(0)
	v_mfma_f32_32x32x16_bf16 v[16:31], v[102:105], v[106:109], v[16:31]
	ds_read_b128 v[106:109], v184 offset:62112
	s_waitcnt lgkmcnt(0)
	v_mfma_f32_32x32x16_bf16 v[0:15], v[102:105], v[106:109], v[0:15]
	ds_read_b128 v[102:105], v183 offset:1216
	ds_read_b128 v[106:109], v184 offset:36032
	s_waitcnt lgkmcnt(0)
	v_mfma_f32_32x32x16_bf16 v[48:63], v[102:105], v[106:109], v[48:63]
	ds_read_b128 v[106:109], v184 offset:44736
	s_waitcnt lgkmcnt(0)
	v_mfma_f32_32x32x16_bf16 v[32:47], v[102:105], v[106:109], v[32:47]
	ds_read_b128 v[106:109], v184 offset:53440
	s_waitcnt lgkmcnt(0)
	v_mfma_f32_32x32x16_bf16 v[16:31], v[102:105], v[106:109], v[16:31]
	ds_read_b128 v[106:109], v184 offset:62144
	s_waitcnt lgkmcnt(0)
	v_mfma_f32_32x32x16_bf16 v[0:15], v[102:105], v[106:109], v[0:15]
	ds_read_b128 v[102:105], v183 offset:1248
	ds_read_b128 v[106:109], v184 offset:36064
	s_waitcnt lgkmcnt(0)
	v_mfma_f32_32x32x16_bf16 v[48:63], v[102:105], v[106:109], v[48:63]
	ds_read_b128 v[106:109], v184 offset:44768
	s_waitcnt lgkmcnt(0)
	v_mfma_f32_32x32x16_bf16 v[32:47], v[102:105], v[106:109], v[32:47]
	ds_read_b128 v[106:109], v184 offset:53472
	s_waitcnt lgkmcnt(0)
	v_mfma_f32_32x32x16_bf16 v[16:31], v[102:105], v[106:109], v[16:31]
	ds_read_b128 v[106:109], v184 offset:62176
	s_waitcnt lgkmcnt(0)
; __device__ __forceinline__ void mix_phase(const int TID, const int BID, PP p, LAS unsigned char* lds) {
;     ...
; #pragma unroll
;         for (int ct = 0; ct < 4; ++ct) {
;             const int cg_ = g * 256 + ch * 128 + ct * 32 + rr; const float gain = p->sgu_v_gain[cg_];
; #pragma unroll
;             for (int r = 0; r < 16; ++r) {
;                 const int i = it_ * 32 + (r & 3) + 8 * (r >> 2) + 4 * g2; const size_t tok = (size_t)n * 128 + i;
;                 const float mixed = gain * acc[ct][r] + p->sgu_b_s[g * 128 + i];
;                 const float uval = __uint_as_float((unsigned)uv[tok * 4096 + cg_] << 16);
	v_mfma_f32_32x32x16_bf16 v[0:15], v[102:105], v[106:109], v[0:15]
	v_lshl_add_u32 v102, s0, 8, v79
	s_load_dwordx2 s[0:1], s[10:11], 0x58
	s_nop 0
	s_load_dwordx2 s[10:11], s[10:11], 0x68
	v_readlane_b32 s20, v254, 38
	v_readlane_b32 s21, v254, 39
	v_lshlrev_b32_e32 v103, 2, v102
	v_or_b32_e32 v104, s72, v70
	v_lshlrev_b32_e32 v104, 2, v104
	v_or_b32_e32 v105, s18, v70
	v_lshlrev_b32_e32 v106, 13, v105
	v_lshl_add_u32 v106, v102, 1, v106
	v_lshlrev_b32_e32 v107, 12, v105
	v_lshl_add_u32 v107, v102, 1, v107
	v_mov_b32_e32 v118, v106
	v_add_u32_e32 v119, 0x2000, v106
	v_add_u32_e32 v120, 0x4000, v106
	v_add_u32_e32 v121, 0x6000, v106
	v_add_u32_e32 v122, 0x10000, v106
	v_add_u32_e32 v123, 0x12000, v106
	v_add_u32_e32 v124, 0x14000, v106
	v_add_u32_e32 v125, 0x16000, v106
	v_add_u32_e32 v126, 0x20000, v106
	v_add_u32_e32 v127, 0x22000, v106
	v_add_u32_e32 v128, 0x24000, v106
	v_add_u32_e32 v129, 0x26000, v106
	v_add_u32_e32 v130, 0x30000, v106
	v_add_u32_e32 v131, 0x32000, v106
	v_add_u32_e32 v132, 0x34000, v106
	v_add_u32_e32 v133, 0x36000, v106
	global_load_ushort v208, v118, s[14:15]
	global_load_ushort v209, v119, s[14:15]
	global_load_ushort v210, v120, s[14:15]
	global_load_ushort v211, v121, s[14:15]
	global_load_ushort v212, v122, s[14:15]
	global_load_ushort v213, v123, s[14:15]
	global_load_ushort v214, v124, s[14:15]
	global_load_ushort v215, v125, s[14:15]
	global_load_ushort v216, v126, s[14:15]
	global_load_ushort v217, v127, s[14:15]
	global_load_ushort v218, v128, s[14:15]
	global_load_ushort v219, v129, s[14:15]
	global_load_ushort v220, v130, s[14:15]
	global_load_ushort v221, v131, s[14:15]
	global_load_ushort v222, v132, s[14:15]
	global_load_ushort v223, v133, s[14:15]
	global_load_ushort v224, v118, s[14:15] offset:64
	global_load_ushort v225, v119, s[14:15] offset:64
	global_load_ushort v226, v120, s[14:15] offset:64
	global_load_ushort v227, v121, s[14:15] offset:64
	global_load_ushort v228, v122, s[14:15] offset:64
	global_load_ushort v229, v123, s[14:15] offset:64
	global_load_ushort v230, v124, s[14:15] offset:64
	global_load_ushort v231, v125, s[14:15] offset:64
	global_load_ushort v232, v126, s[14:15] offset:64
	global_load_ushort v233, v127, s[14:15] offset:64
	global_load_ushort v234, v128, s[14:15] offset:64
	global_load_ushort v235, v129, s[14:15] offset:64
	global_load_ushort v236, v130, s[14:15] offset:64
	global_load_ushort v237, v131, s[14:15] offset:64
	global_load_ushort v238, v132, s[14:15] offset:64
	global_load_ushort v239, v133, s[14:15] offset:64
	s_waitcnt lgkmcnt(0)
	global_load_dword v110, v103, s[0:1]
	global_load_dword v111, v103, s[0:1] offset:128
	global_load_dword v112, v103, s[0:1] offset:256
	global_load_dword v113, v103, s[0:1] offset:384
	global_load_dword v166, v104, s[10:11]
	global_load_dword v167, v104, s[10:11] offset:4
	global_load_dword v168, v104, s[10:11] offset:8
	global_load_dword v169, v104, s[10:11] offset:12
	global_load_dword v170, v104, s[10:11] offset:32
	global_load_dword v171, v104, s[10:11] offset:36
	global_load_dword v172, v104, s[10:11] offset:40
	global_load_dword v173, v104, s[10:11] offset:44
	global_load_dword v174, v104, s[10:11] offset:64
	global_load_dword v175, v104, s[10:11] offset:68
	global_load_dword v176, v104, s[10:11] offset:72
	global_load_dword v177, v104, s[10:11] offset:76
	global_load_dword v178, v104, s[10:11] offset:96
	global_load_dword v179, v104, s[10:11] offset:100
	global_load_dword v180, v104, s[10:11] offset:104
	global_load_dword v181, v104, s[10:11] offset:108
	v_mov_b32_e32 v134, v107
	v_add_u32_e32 v135, 0x1000, v107
	v_add_u32_e32 v136, 0x2000, v107
	v_add_u32_e32 v137, 0x3000, v107
	v_add_u32_e32 v138, 0x8000, v107
	v_add_u32_e32 v139, 0x9000, v107
	v_add_u32_e32 v140, 0xa000, v107
	v_add_u32_e32 v141, 0xb000, v107
	v_add_u32_e32 v142, 0x10000, v107
	v_add_u32_e32 v143, 0x11000, v107
	v_add_u32_e32 v144, 0x12000, v107
	v_add_u32_e32 v145, 0x13000, v107
	v_add_u32_e32 v146, 0x18000, v107
	v_add_u32_e32 v147, 0x19000, v107
	v_add_u32_e32 v148, 0x1a000, v107
	v_add_u32_e32 v149, 0x1b000, v107
	s_waitcnt vmcnt(0)
	global_load_ushort v240, v118, s[14:15] offset:128
	global_load_ushort v241, v119, s[14:15] offset:128
	global_load_ushort v242, v120, s[14:15] offset:128
	global_load_ushort v243, v121, s[14:15] offset:128
	global_load_ushort v244, v122, s[14:15] offset:128
	global_load_ushort v245, v123, s[14:15] offset:128
	global_load_ushort v246, v124, s[14:15] offset:128
	global_load_ushort v247, v125, s[14:15] offset:128
	global_load_ushort v248, v126, s[14:15] offset:128
	global_load_ushort v249, v127, s[14:15] offset:128
	global_load_ushort v250, v128, s[14:15] offset:128
	global_load_ushort v251, v129, s[14:15] offset:128
	global_load_ushort v252, v130, s[14:15] offset:128
	global_load_ushort v253, v131, s[14:15] offset:128
	global_load_ushort v198, v132, s[14:15] offset:128
	global_load_ushort v199, v133, s[14:15] offset:128
	global_load_ushort v150, v118, s[14:15] offset:192
	global_load_ushort v151, v119, s[14:15] offset:192
	global_load_ushort v152, v120, s[14:15] offset:192
	global_load_ushort v153, v121, s[14:15] offset:192
	global_load_ushort v154, v122, s[14:15] offset:192
	global_load_ushort v155, v123, s[14:15] offset:192
	global_load_ushort v156, v124, s[14:15] offset:192
	global_load_ushort v157, v125, s[14:15] offset:192
	global_load_ushort v158, v126, s[14:15] offset:192
	global_load_ushort v159, v127, s[14:15] offset:192
	global_load_ushort v114, v128, s[14:15] offset:192
	global_load_ushort v115, v129, s[14:15] offset:192
	global_load_ushort v196, v130, s[14:15] offset:192
	global_load_ushort v197, v131, s[14:15] offset:192
; __device__ __forceinline__ unsigned cvt_pk_bf16(float lo, float hi) { unsigned r; asm volatile("v_cvt_pk_bf16_f32 %0, %1, %2" : "=v"(r) : "v"(lo), "v"(hi)); return r; }
; __device__ __forceinline__ void mix_phase(const int TID, const int BID, PP p, LAS unsigned char* lds) {
;     ...
; #pragma unroll
;         for (int ct = 0; ct < 4; ++ct) {
;             const int cg_ = g * 256 + ch * 128 + ct * 32 + rr; const float gain = p->sgu_v_gain[cg_];
; #pragma unroll
;             for (int r = 0; r < 16; ++r) {
;                 const int i = it_ * 32 + (r & 3) + 8 * (r >> 2) + 4 * g2; const size_t tok = (size_t)n * 128 + i;
;                 const float mixed = gain * acc[ct][r] + p->sgu_b_s[g * 128 + i];
;                 const float uval = __uint_as_float((unsigned)uv[tok * 4096 + cg_] << 16);
;                 AB[tok * 2048 + cg_] = (bf16_t)(cvt_pk_bf16(uval * mixed, 0.f) & 0xffffu);
;             }
	global_load_ushort v200, v132, s[14:15] offset:192
	global_load_ushort v201, v133, s[14:15] offset:192
	v_fma_f32 v48, v48, v110, v166
	v_fma_f32 v49, v49, v110, v167
	v_fma_f32 v50, v50, v110, v168
	v_fma_f32 v51, v51, v110, v169
	v_fma_f32 v52, v52, v110, v170
	v_fma_f32 v53, v53, v110, v171
	v_fma_f32 v54, v54, v110, v172
	v_fma_f32 v55, v55, v110, v173
	v_fma_f32 v56, v56, v110, v174
	v_fma_f32 v57, v57, v110, v175
	v_fma_f32 v58, v58, v110, v176
	v_fma_f32 v59, v59, v110, v177
	v_fma_f32 v60, v60, v110, v178
	v_fma_f32 v61, v61, v110, v179
	v_fma_f32 v62, v62, v110, v180
	v_fma_f32 v63, v63, v110, v181
	v_fma_f32 v32, v32, v111, v166
	v_fma_f32 v33, v33, v111, v167
	v_fma_f32 v34, v34, v111, v168
	v_fma_f32 v35, v35, v111, v169
	v_fma_f32 v36, v36, v111, v170
	v_fma_f32 v37, v37, v111, v171
	v_fma_f32 v38, v38, v111, v172
	v_fma_f32 v39, v39, v111, v173
	v_fma_f32 v40, v40, v111, v174
	v_fma_f32 v41, v41, v111, v175
	v_fma_f32 v42, v42, v111, v176
	v_fma_f32 v43, v43, v111, v177
	v_fma_f32 v44, v44, v111, v178
	v_fma_f32 v45, v45, v111, v179
	v_fma_f32 v46, v46, v111, v180
	v_fma_f32 v47, v47, v111, v181
	v_fma_f32 v16, v16, v112, v166
	v_fma_f32 v17, v17, v112, v167
	v_fma_f32 v18, v18, v112, v168
	v_fma_f32 v19, v19, v112, v169
	v_fma_f32 v20, v20, v112, v170
	v_fma_f32 v21, v21, v112, v171
	v_fma_f32 v22, v22, v112, v172
	v_fma_f32 v23, v23, v112, v173
	v_fma_f32 v24, v24, v112, v174
	v_fma_f32 v25, v25, v112, v175
	v_fma_f32 v26, v26, v112, v176
	v_fma_f32 v27, v27, v112, v177
	v_fma_f32 v28, v28, v112, v178
	v_fma_f32 v29, v29, v112, v179
	v_fma_f32 v30, v30, v112, v180
	v_fma_f32 v31, v31, v112, v181
	v_fma_f32 v0, v0, v113, v166
	v_fma_f32 v1, v1, v113, v167
	v_fma_f32 v2, v2, v113, v168
	v_fma_f32 v3, v3, v113, v169
	v_fma_f32 v4, v4, v113, v170
	v_fma_f32 v5, v5, v113, v171
	v_fma_f32 v6, v6, v113, v172
	v_fma_f32 v7, v7, v113, v173
	v_fma_f32 v8, v8, v113, v174
	v_fma_f32 v9, v9, v113, v175
	v_fma_f32 v10, v10, v113, v176
	v_fma_f32 v11, v11, v113, v177
	v_fma_f32 v12, v12, v113, v178
	v_fma_f32 v13, v13, v113, v179
	v_fma_f32 v14, v14, v113, v180
	v_fma_f32 v15, v15, v113, v181
	v_lshlrev_b32_e32 v208, 16, v208
	v_mul_f32_e32 v208, v48, v208
	v_cvt_pk_bf16_f32 v208, v208, v161
	v_lshlrev_b32_e32 v209, 16, v209
	v_mul_f32_e32 v209, v49, v209
	v_cvt_pk_bf16_f32 v209, v209, v161
	v_lshlrev_b32_e32 v210, 16, v210
	v_mul_f32_e32 v210, v50, v210
	v_cvt_pk_bf16_f32 v210, v210, v161
	v_lshlrev_b32_e32 v211, 16, v211
	v_mul_f32_e32 v211, v51, v211
	v_cvt_pk_bf16_f32 v211, v211, v161
	v_lshlrev_b32_e32 v212, 16, v212
	v_mul_f32_e32 v212, v52, v212
	v_cvt_pk_bf16_f32 v212, v212, v161
	v_lshlrev_b32_e32 v213, 16, v213
	v_mul_f32_e32 v213, v53, v213
	v_cvt_pk_bf16_f32 v213, v213, v161
	v_lshlrev_b32_e32 v214, 16, v214
	v_mul_f32_e32 v214, v54, v214
	v_cvt_pk_bf16_f32 v214, v214, v161
	v_lshlrev_b32_e32 v215, 16, v215
	v_mul_f32_e32 v215, v55, v215
	v_cvt_pk_bf16_f32 v215, v215, v161
	v_lshlrev_b32_e32 v216, 16, v216
	v_mul_f32_e32 v216, v56, v216
	v_cvt_pk_bf16_f32 v216, v216, v161
	v_lshlrev_b32_e32 v217, 16, v217
	v_mul_f32_e32 v217, v57, v217
	v_cvt_pk_bf16_f32 v217, v217, v161
	v_lshlrev_b32_e32 v218, 16, v218
	v_mul_f32_e32 v218, v58, v218
	v_cvt_pk_bf16_f32 v218, v218, v161
	v_lshlrev_b32_e32 v219, 16, v219
	v_mul_f32_e32 v219, v59, v219
	v_cvt_pk_bf16_f32 v219, v219, v161
	v_lshlrev_b32_e32 v220, 16, v220
	v_mul_f32_e32 v220, v60, v220
	v_cvt_pk_bf16_f32 v220, v220, v161
	v_lshlrev_b32_e32 v221, 16, v221
	v_mul_f32_e32 v221, v61, v221
	v_cvt_pk_bf16_f32 v221, v221, v161
	v_lshlrev_b32_e32 v222, 16, v222
	v_mul_f32_e32 v222, v62, v222
	v_cvt_pk_bf16_f32 v222, v222, v161
	v_lshlrev_b32_e32 v223, 16, v223
	v_mul_f32_e32 v223, v63, v223
	v_cvt_pk_bf16_f32 v223, v223, v161
	global_store_short v134, v208, s[20:21]
	global_store_short v135, v209, s[20:21]
	global_store_short v136, v210, s[20:21]
	global_store_short v137, v211, s[20:21]
	global_store_short v138, v212, s[20:21]
	global_store_short v139, v213, s[20:21]
	global_store_short v140, v214, s[20:21]
	global_store_short v141, v215, s[20:21]
	global_store_short v142, v216, s[20:21]
	global_store_short v143, v217, s[20:21]
	global_store_short v144, v218, s[20:21]
	global_store_short v145, v219, s[20:21]
	global_store_short v146, v220, s[20:21]
	global_store_short v147, v221, s[20:21]
	global_store_short v148, v222, s[20:21]
	global_store_short v149, v223, s[20:21]
	s_waitcnt vmcnt(40)
; __device__ __forceinline__ unsigned cvt_pk_bf16(float lo, float hi) { unsigned r; asm volatile("v_cvt_pk_bf16_f32 %0, %1, %2" : "=v"(r) : "v"(lo), "v"(hi)); return r; }
; __device__ __forceinline__ void mix_phase(const int TID, const int BID, PP p, LAS unsigned char* lds) {
;     ...
;         for (int ct = 0; ct < 4; ++ct) {
;             const int cg_ = g * 256 + ch * 128 + ct * 32 + rr; const float gain = p->sgu_v_gain[cg_];
; #pragma unroll
;             for (int r = 0; r < 16; ++r) {
;                 const int i = it_ * 32 + (r & 3) + 8 * (r >> 2) + 4 * g2; const size_t tok = (size_t)n * 128 + i;
;                 const float mixed = gain * acc[ct][r] + p->sgu_b_s[g * 128 + i];
;                 const float uval = __uint_as_float((unsigned)uv[tok * 4096 + cg_] << 16);
;                 AB[tok * 2048 + cg_] = (bf16_t)(cvt_pk_bf16(uval * mixed, 0.f) & 0xffffu);
;             }
	v_lshlrev_b32_e32 v224, 16, v224
	v_mul_f32_e32 v224, v32, v224
	v_cvt_pk_bf16_f32 v224, v224, v161
	v_lshlrev_b32_e32 v225, 16, v225
	v_mul_f32_e32 v225, v33, v225
	v_cvt_pk_bf16_f32 v225, v225, v161
	v_lshlrev_b32_e32 v226, 16, v226
	v_mul_f32_e32 v226, v34, v226
	v_cvt_pk_bf16_f32 v226, v226, v161
	v_lshlrev_b32_e32 v227, 16, v227
	v_mul_f32_e32 v227, v35, v227
	v_cvt_pk_bf16_f32 v227, v227, v161
	v_lshlrev_b32_e32 v228, 16, v228
	v_mul_f32_e32 v228, v36, v228
	v_cvt_pk_bf16_f32 v228, v228, v161
	v_lshlrev_b32_e32 v229, 16, v229
	v_mul_f32_e32 v229, v37, v229
	v_cvt_pk_bf16_f32 v229, v229, v161
	v_lshlrev_b32_e32 v230, 16, v230
	v_mul_f32_e32 v230, v38, v230
	v_cvt_pk_bf16_f32 v230, v230, v161
	v_lshlrev_b32_e32 v231, 16, v231
	v_mul_f32_e32 v231, v39, v231
	v_cvt_pk_bf16_f32 v231, v231, v161
	v_lshlrev_b32_e32 v232, 16, v232
	v_mul_f32_e32 v232, v40, v232
	v_cvt_pk_bf16_f32 v232, v232, v161
	v_lshlrev_b32_e32 v233, 16, v233
	v_mul_f32_e32 v233, v41, v233
	v_cvt_pk_bf16_f32 v233, v233, v161
	v_lshlrev_b32_e32 v234, 16, v234
	v_mul_f32_e32 v234, v42, v234
	v_cvt_pk_bf16_f32 v234, v234, v161
	v_lshlrev_b32_e32 v235, 16, v235
	v_mul_f32_e32 v235, v43, v235
	v_cvt_pk_bf16_f32 v235, v235, v161
	v_lshlrev_b32_e32 v236, 16, v236
	v_mul_f32_e32 v236, v44, v236
	v_cvt_pk_bf16_f32 v236, v236, v161
	v_lshlrev_b32_e32 v237, 16, v237
	v_mul_f32_e32 v237, v45, v237
	v_cvt_pk_bf16_f32 v237, v237, v161
	v_lshlrev_b32_e32 v238, 16, v238
	v_mul_f32_e32 v238, v46, v238
	v_cvt_pk_bf16_f32 v238, v238, v161
	v_lshlrev_b32_e32 v239, 16, v239
	v_mul_f32_e32 v239, v47, v239
	v_cvt_pk_bf16_f32 v239, v239, v161
	global_store_short v134, v224, s[20:21] offset:64
	global_store_short v135, v225, s[20:21] offset:64
	global_store_short v136, v226, s[20:21] offset:64
	global_store_short v137, v227, s[20:21] offset:64
	global_store_short v138, v228, s[20:21] offset:64
	global_store_short v139, v229, s[20:21] offset:64
	global_store_short v140, v230, s[20:21] offset:64
	global_store_short v141, v231, s[20:21] offset:64
	global_store_short v142, v232, s[20:21] offset:64
	global_store_short v143, v233, s[20:21] offset:64
	global_store_short v144, v234, s[20:21] offset:64
	global_store_short v145, v235, s[20:21] offset:64
	global_store_short v146, v236, s[20:21] offset:64
	global_store_short v147, v237, s[20:21] offset:64
	global_store_short v148, v238, s[20:21] offset:64
	global_store_short v149, v239, s[20:21] offset:64
	s_waitcnt vmcnt(32)
	v_lshlrev_b32_e32 v240, 16, v240
	v_mul_f32_e32 v240, v16, v240
	v_cvt_pk_bf16_f32 v240, v240, v161
	v_lshlrev_b32_e32 v241, 16, v241
	v_mul_f32_e32 v241, v17, v241
	v_cvt_pk_bf16_f32 v241, v241, v161
	v_lshlrev_b32_e32 v242, 16, v242
	v_mul_f32_e32 v242, v18, v242
	v_cvt_pk_bf16_f32 v242, v242, v161
	v_lshlrev_b32_e32 v243, 16, v243
	v_mul_f32_e32 v243, v19, v243
	v_cvt_pk_bf16_f32 v243, v243, v161
	v_lshlrev_b32_e32 v244, 16, v244
	v_mul_f32_e32 v244, v20, v244
	v_cvt_pk_bf16_f32 v244, v244, v161
	v_lshlrev_b32_e32 v245, 16, v245
	v_mul_f32_e32 v245, v21, v245
	v_cvt_pk_bf16_f32 v245, v245, v161
	v_lshlrev_b32_e32 v246, 16, v246
	v_mul_f32_e32 v246, v22, v246
	v_cvt_pk_bf16_f32 v246, v246, v161
	v_lshlrev_b32_e32 v247, 16, v247
	v_mul_f32_e32 v247, v23, v247
	v_cvt_pk_bf16_f32 v247, v247, v161
	v_lshlrev_b32_e32 v248, 16, v248
	v_mul_f32_e32 v248, v24, v248
	v_cvt_pk_bf16_f32 v248, v248, v161
	v_lshlrev_b32_e32 v249, 16, v249
	v_mul_f32_e32 v249, v25, v249
	v_cvt_pk_bf16_f32 v249, v249, v161
	v_lshlrev_b32_e32 v250, 16, v250
	v_mul_f32_e32 v250, v26, v250
	v_cvt_pk_bf16_f32 v250, v250, v161
	v_lshlrev_b32_e32 v251, 16, v251
	v_mul_f32_e32 v251, v27, v251
	v_cvt_pk_bf16_f32 v251, v251, v161
	v_lshlrev_b32_e32 v252, 16, v252
	v_mul_f32_e32 v252, v28, v252
	v_cvt_pk_bf16_f32 v252, v252, v161
	v_lshlrev_b32_e32 v253, 16, v253
	v_mul_f32_e32 v253, v29, v253
	v_cvt_pk_bf16_f32 v253, v253, v161
	v_lshlrev_b32_e32 v198, 16, v198
	v_mul_f32_e32 v198, v30, v198
	v_cvt_pk_bf16_f32 v198, v198, v161
	v_lshlrev_b32_e32 v199, 16, v199
	v_mul_f32_e32 v199, v31, v199
	v_cvt_pk_bf16_f32 v199, v199, v161
	global_store_short v134, v240, s[20:21] offset:128
	global_store_short v135, v241, s[20:21] offset:128
	global_store_short v136, v242, s[20:21] offset:128
	global_store_short v137, v243, s[20:21] offset:128
	global_store_short v138, v244, s[20:21] offset:128
	global_store_short v139, v245, s[20:21] offset:128
	global_store_short v140, v246, s[20:21] offset:128
	global_store_short v141, v247, s[20:21] offset:128
	global_store_short v142, v248, s[20:21] offset:128
	global_store_short v143, v249, s[20:21] offset:128
	global_store_short v144, v250, s[20:21] offset:128
	global_store_short v145, v251, s[20:21] offset:128
	global_store_short v146, v252, s[20:21] offset:128
	global_store_short v147, v253, s[20:21] offset:128
	global_store_short v148, v198, s[20:21] offset:128
	global_store_short v149, v199, s[20:21] offset:128
	s_waitcnt vmcnt(47)
; __device__ __forceinline__ unsigned cvt_pk_bf16(float lo, float hi) { unsigned r; asm volatile("v_cvt_pk_bf16_f32 %0, %1, %2" : "=v"(r) : "v"(lo), "v"(hi)); return r; }
; __device__ __forceinline__ void mix_phase(const int TID, const int BID, PP p, LAS unsigned char* lds) {
;     ...
;         for (int ct = 0; ct < 4; ++ct) {
;             const int cg_ = g * 256 + ch * 128 + ct * 32 + rr; const float gain = p->sgu_v_gain[cg_];
; #pragma unroll
;             for (int r = 0; r < 16; ++r) {
;                 const int i = it_ * 32 + (r & 3) + 8 * (r >> 2) + 4 * g2; const size_t tok = (size_t)n * 128 + i;
;                 const float mixed = gain * acc[ct][r] + p->sgu_b_s[g * 128 + i];
;                 const float uval = __uint_as_float((unsigned)uv[tok * 4096 + cg_] << 16);
;                 AB[tok * 2048 + cg_] = (bf16_t)(cvt_pk_bf16(uval * mixed, 0.f) & 0xffffu);
;             }
	v_lshlrev_b32_e32 v150, 16, v150
	v_mul_f32_e32 v150, v0, v150
	v_cvt_pk_bf16_f32 v150, v150, v161
	v_lshlrev_b32_e32 v151, 16, v151
	v_mul_f32_e32 v151, v1, v151
	v_cvt_pk_bf16_f32 v151, v151, v161
	v_lshlrev_b32_e32 v152, 16, v152
	v_mul_f32_e32 v152, v2, v152
	v_cvt_pk_bf16_f32 v152, v152, v161
	v_lshlrev_b32_e32 v153, 16, v153
	v_mul_f32_e32 v153, v3, v153
	v_cvt_pk_bf16_f32 v153, v153, v161
	v_lshlrev_b32_e32 v154, 16, v154
	v_mul_f32_e32 v154, v4, v154
	v_cvt_pk_bf16_f32 v154, v154, v161
	v_lshlrev_b32_e32 v155, 16, v155
	v_mul_f32_e32 v155, v5, v155
	v_cvt_pk_bf16_f32 v155, v155, v161
	v_lshlrev_b32_e32 v156, 16, v156
	v_mul_f32_e32 v156, v6, v156
	v_cvt_pk_bf16_f32 v156, v156, v161
	v_lshlrev_b32_e32 v157, 16, v157
	v_mul_f32_e32 v157, v7, v157
	v_cvt_pk_bf16_f32 v157, v157, v161
	v_lshlrev_b32_e32 v158, 16, v158
	v_mul_f32_e32 v158, v8, v158
	v_cvt_pk_bf16_f32 v158, v158, v161
	v_lshlrev_b32_e32 v159, 16, v159
	v_mul_f32_e32 v159, v9, v159
	v_cvt_pk_bf16_f32 v159, v159, v161
	v_lshlrev_b32_e32 v114, 16, v114
	v_mul_f32_e32 v114, v10, v114
	v_cvt_pk_bf16_f32 v114, v114, v161
	v_lshlrev_b32_e32 v115, 16, v115
	v_mul_f32_e32 v115, v11, v115
	v_cvt_pk_bf16_f32 v115, v115, v161
	v_lshlrev_b32_e32 v196, 16, v196
	v_mul_f32_e32 v196, v12, v196
	v_cvt_pk_bf16_f32 v196, v196, v161
	v_lshlrev_b32_e32 v197, 16, v197
	v_mul_f32_e32 v197, v13, v197
	v_cvt_pk_bf16_f32 v197, v197, v161
	v_lshlrev_b32_e32 v200, 16, v200
	v_mul_f32_e32 v200, v14, v200
	v_cvt_pk_bf16_f32 v200, v200, v161
	v_lshlrev_b32_e32 v201, 16, v201
	v_mul_f32_e32 v201, v15, v201
	v_cvt_pk_bf16_f32 v201, v201, v161
	global_store_short v134, v150, s[20:21] offset:192
	global_store_short v135, v151, s[20:21] offset:192
	global_store_short v136, v152, s[20:21] offset:192
	global_store_short v137, v153, s[20:21] offset:192
	global_store_short v138, v154, s[20:21] offset:192
	global_store_short v139, v155, s[20:21] offset:192
	global_store_short v140, v156, s[20:21] offset:192
	global_store_short v141, v157, s[20:21] offset:192
	global_store_short v142, v158, s[20:21] offset:192
	global_store_short v143, v159, s[20:21] offset:192
	global_store_short v144, v114, s[20:21] offset:192
	global_store_short v145, v115, s[20:21] offset:192
	global_store_short v146, v196, s[20:21] offset:192
	global_store_short v147, v197, s[20:21] offset:192
	global_store_short v148, v200, s[20:21] offset:192
	global_store_short v149, v201, s[20:21] offset:192
	s_cbranch_scc1 .LBB0_845

; #define LAS __attribute__((address_space(3)))
; __device__ __forceinline__ unsigned cvt_pk_bf16(float lo, float hi) { unsigned r; asm volatile("v_cvt_pk_bf16_f32 %0, %1, %2" : "=v"(r) : "v"(lo), "v"(hi)); return r; }
; __device__ __forceinline__ void mix_phase(const int TID, const int BID, PP p, LAS unsigned char* lds) {
;     ...
;         { const int i = t >> 2, jseg = (t & 3) * 32; const float* wsrc = p->sgu_w_s + ((size_t)g * 128 + i) * 128 + jseg;
; #pragma unroll
;           for (int q = 0; q < 4; ++q) {
;               f32x4 a = *(const f32x4*)(wsrc + q * 8), bq = *(const f32x4*)(wsrc + q * 8 + 4);
;               const int j0 = jseg + q * 8; const bool ok = (j0 >> 6) <= (i >> 6);
;               u32x4 w;
;               if (ok) { w.x = cvt_pk_bf16(a[0] * rinv[j0], a[1] * rinv[j0 + 1]); w.y = cvt_pk_bf16(a[2] * rinv[j0 + 2], a[3] * rinv[j0 + 3]);
;                         w.z = cvt_pk_bf16(bq[0] * rinv[j0 + 4], bq[1] * rinv[j0 + 5]); w.w = cvt_pk_bf16(bq[2] * rinv[j0 + 6], bq[3] * rinv[j0 + 7]); }
;               else w = (u32x4){0u, 0u, 0u, 0u};
;               *(LAS u32x4*)(Wsl + i * 272 + j0 * 2) = w;
;           } }
.LBB0_837:
	s_or_b64 exec, exec, s[20:21]
	s_and_b32 s0, s22, 7
	s_lshl_b32 s72, s0, 7
	v_lshl_add_u64 v[0:1], s[72:73], 0, v[64:65]
	v_lshlrev_b64 v[0:1], 9, v[0:1]
	v_lshl_add_u64 v[4:5], v[66:67], 0, v[0:1]
	global_load_dwordx4 v[118:121], v[4:5], off
	global_load_dwordx4 v[122:125], v[4:5], off offset:16
	global_load_dwordx4 v[126:129], v[4:5], off offset:32
	global_load_dwordx4 v[130:133], v[4:5], off offset:48
	global_load_dwordx4 v[134:137], v[4:5], off offset:64
	global_load_dwordx4 v[138:141], v[4:5], off offset:80
	global_load_dwordx4 v[142:145], v[4:5], off offset:96
	global_load_dwordx4 v[146:149], v[4:5], off offset:112
	v_add_u32_e32 v6, v73, v83
	s_waitcnt lgkmcnt(0)
	s_barrier
	s_and_saveexec_b64 s[10:11], s[8:9]
	s_xor_b64 s[10:11], exec, s[10:11]
	s_cbranch_execz .LBB0_839
	s_waitcnt vmcnt(0)
	v_mov_b64_e32 v[0:1], v[122:123]
	v_mov_b64_e32 v[2:3], v[124:125]
	s_waitcnt vmcnt(0)
	v_mov_b64_e32 v[8:9], v[118:119]
	v_mov_b64_e32 v[10:11], v[120:121]
	ds_read2_b32 v[12:13], v81 offset1:1
	s_waitcnt vmcnt(0) lgkmcnt(0)
	v_mul_f32_e32 v7, v8, v12
	v_mul_f32_e32 v8, v9, v13
	v_cvt_pk_bf16_f32 v8, v7, v8
	ds_read2_b32 v[12:13], v81 offset0:2 offset1:3
	s_waitcnt lgkmcnt(0)
	v_mul_f32_e32 v9, v11, v13
	v_mul_f32_e32 v7, v10, v12
	v_cvt_pk_bf16_f32 v9, v7, v9
	ds_read2_b32 v[10:11], v81 offset0:4 offset1:5
	s_waitcnt lgkmcnt(0)
	v_mul_f32_e32 v0, v0, v10
	v_mul_f32_e32 v1, v1, v11
	v_cvt_pk_bf16_f32 v10, v0, v1
	ds_read2_b32 v[0:1], v81 offset0:6 offset1:7
	s_waitcnt lgkmcnt(0)
	v_mul_f32_e32 v0, v2, v0
	v_mul_f32_e32 v1, v3, v1
	v_cvt_pk_bf16_f32 v11, v0, v1
	ds_write_b128 v6, v[8:11] offset:1024
	s_waitcnt vmcnt(0)
	v_mov_b64_e32 v[6:7], v[130:131]
	v_mov_b64_e32 v[8:9], v[132:133]
	s_waitcnt vmcnt(0)
	v_mov_b64_e32 v[0:1], v[126:127]
	v_mov_b64_e32 v[2:3], v[128:129]
	ds_read2_b32 v[10:11], v81 offset0:8 offset1:9
	s_waitcnt vmcnt(0) lgkmcnt(0)
	v_mul_f32_e32 v0, v0, v10
	v_mul_f32_e32 v1, v1, v11
	v_cvt_pk_bf16_f32 v0, v0, v1
	ds_read2_b32 v[10:11], v81 offset0:10 offset1:11
	s_waitcnt lgkmcnt(0)
	v_mul_f32_e32 v1, v2, v10
	v_mul_f32_e32 v2, v3, v11
	v_cvt_pk_bf16_f32 v1, v1, v2
	ds_read2_b32 v[2:3], v81 offset0:12 offset1:13
	s_waitcnt lgkmcnt(0)
	v_mul_f32_e32 v2, v6, v2
	v_mul_f32_e32 v3, v7, v3
	v_cvt_pk_bf16_f32 v2, v2, v3
	ds_read2_b32 v[6:7], v81 offset0:14 offset1:15
	s_waitcnt lgkmcnt(0)
	v_mul_f32_e32 v3, v8, v6
	v_mul_f32_e32 v6, v9, v7
	v_cvt_pk_bf16_f32 v3, v3, v6
.LBB0_839:
	s_andn2_saveexec_b64 s[10:11], s[10:11]
	v_mov_b32_e32 v0, 0
	v_mov_b32_e32 v1, v0
	v_mov_b32_e32 v2, v0
	v_mov_b32_e32 v3, v0
	ds_write_b128 v6, v[202:205] offset:1024
	s_or_b64 exec, exec, s[10:11]
	ds_write_b128 v87, v[0:3] offset:1024
	s_and_saveexec_b64 s[10:11], s[8:9]
	s_xor_b64 s[10:11], exec, s[10:11]
	s_cbranch_execz .LBB0_843
	s_waitcnt vmcnt(0)
	v_mov_b64_e32 v[0:1], v[138:139]
	v_mov_b64_e32 v[2:3], v[140:141]
	s_waitcnt vmcnt(0)
	v_mov_b64_e32 v[6:7], v[134:135]
	v_mov_b64_e32 v[8:9], v[136:137]
	ds_read2_b32 v[10:11], v81 offset0:16 offset1:17
	s_waitcnt vmcnt(0) lgkmcnt(0)
	v_mul_f32_e32 v6, v6, v10
	v_mul_f32_e32 v7, v7, v11
	v_cvt_pk_bf16_f32 v6, v6, v7
	ds_read2_b32 v[10:11], v81 offset0:18 offset1:19
	s_waitcnt lgkmcnt(0)
	v_mul_f32_e32 v7, v8, v10
	v_mul_f32_e32 v8, v9, v11
	v_cvt_pk_bf16_f32 v7, v7, v8
	ds_read2_b32 v[8:9], v81 offset0:20 offset1:21
	s_waitcnt lgkmcnt(0)
	v_mul_f32_e32 v0, v0, v8
	v_mul_f32_e32 v1, v1, v9
	v_cvt_pk_bf16_f32 v8, v0, v1
	ds_read2_b32 v[0:1], v81 offset0:22 offset1:23
	s_waitcnt lgkmcnt(0)
	v_mul_f32_e32 v0, v2, v0
	v_mul_f32_e32 v1, v3, v1
	v_cvt_pk_bf16_f32 v9, v0, v1
	ds_write_b128 v185, v[6:9] offset:1024
	s_waitcnt vmcnt(0)
	v_mov_b64_e32 v[6:7], v[146:147]
	v_mov_b64_e32 v[8:9], v[148:149]
	s_waitcnt vmcnt(0)
	v_mov_b64_e32 v[0:1], v[142:143]
	v_mov_b64_e32 v[2:3], v[144:145]
	ds_read2_b32 v[4:5], v81 offset0:24 offset1:25
	s_waitcnt vmcnt(0) lgkmcnt(0)
	v_mul_f32_e32 v0, v0, v4
	v_mul_f32_e32 v1, v1, v5
	v_cvt_pk_bf16_f32 v0, v0, v1
	ds_read2_b32 v[4:5], v81 offset0:26 offset1:27
	s_waitcnt lgkmcnt(0)
	v_mul_f32_e32 v1, v2, v4
	v_mul_f32_e32 v2, v3, v5
	v_cvt_pk_bf16_f32 v1, v1, v2
	ds_read2_b32 v[2:3], v81 offset0:28 offset1:29
	s_waitcnt lgkmcnt(0)
	v_mul_f32_e32 v2, v6, v2
	v_mul_f32_e32 v3, v7, v3
	v_cvt_pk_bf16_f32 v2, v2, v3
	ds_read2_b32 v[4:5], v81 offset0:30 offset1:31
	s_waitcnt lgkmcnt(0)
	v_mul_f32_e32 v3, v8, v4
	v_mul_f32_e32 v4, v9, v5
	v_cvt_pk_bf16_f32 v3, v3, v4
